# grid seams: early unwaited L2 write-back by the workgroups with 4 and 1 arrivals still outstanding on their XCD
# baseline (speedup 1.0000x reference)
; __device__ __forceinline__ unsigned xb_ld(unsigned* p)              { return __hip_atomic_load(p, __ATOMIC_RELAXED, __HIP_MEMORY_SCOPE_AGENT); }
; __device__ __forceinline__ unsigned xb_add(unsigned* p, unsigned v) { return __hip_atomic_fetch_add(p, v, __ATOMIC_RELAXED, __HIP_MEMORY_SCOPE_AGENT); }
; #define XB_SPIN(cond, bar) do { unsigned _sp = 0; while (cond) { __builtin_amdgcn_s_sleep(1); \
;     if ((++_sp & 255u) == 0u) { if (xb_ld(&(bar)[XB_TMO])) break; if (_sp > XB_SPIN_CAP) { atomicAdd(&(bar)[XB_TMO], 1u); break; } } } } while (0)
; __device__ __forceinline__ void xcd_barrier(const XcdBarrier& b, const int wv) {
;     ...
;         const unsigned old = xb_add(&bar[XB_XSUB(b.x)], 1u);
;         const unsigned gen = old / nloc;
;         if (old + 1u == (gen + 1u) * nloc) {
;             __builtin_amdgcn_fence(__ATOMIC_RELEASE, "agent");
;             asm volatile("s_waitcnt vmcnt(0)" ::: "memory");
;             const unsigned og = xb_add(&bar[XB_TOP], 1u);
;             const unsigned tg = og / nx;
;             if (og + 1u == (tg + 1u) * nx) xb_add(&bar[XB_TOPGEN], 1u);
;             else XB_SPIN(xb_ld(&bar[XB_TOPGEN]) == tg, bar);
;             __builtin_amdgcn_fence(__ATOMIC_ACQUIRE, "agent");
;             xb_add(&bar[XB_XGEN(b.x)], 1u);
;             asm volatile("s_waitcnt vmcnt(0)" ::: "memory");
;         } else {
;             XB_SPIN(xb_ld(&bar[XB_XGEN(b.x)]) == gen, bar);
;             __builtin_amdgcn_fence(__ATOMIC_ACQUIRE, "agent");
;             asm volatile("s_waitcnt vmcnt(0)" ::: "memory");
;         }
.Lseam1_328:
	s_or_b64 exec, exec, s[14:15]
	v_cvt_f32_u32_e32 v4, v2
	s_waitcnt vmcnt(0)
	v_readfirstlane_b32 s3, v3
	v_sub_u32_e32 v3, 0, v2
	v_rcp_iflag_f32_e32 v4, v4
	v_add_u32_e32 v5, s3, v1
	v_mul_f32_e32 v4, 0x4f7ffffe, v4
	v_cvt_u32_f32_e32 v4, v4
	v_mul_lo_u32 v1, v3, v4
	v_mul_hi_u32 v1, v4, v1
	v_add_u32_e32 v1, v4, v1
	v_mul_hi_u32 v1, v5, v1
	v_mul_lo_u32 v3, v1, v2
	v_sub_u32_e32 v3, v5, v3
	v_add_u32_e32 v4, 1, v1
	v_cmp_ge_u32_e32 vcc, v3, v2
	s_nop 1
	v_cndmask_b32_e32 v1, v1, v4, vcc
	v_sub_u32_e32 v4, v3, v2
	v_cndmask_b32_e32 v3, v3, v4, vcc
	v_add_u32_e32 v4, 1, v1
	v_cmp_ge_u32_e32 vcc, v3, v2
	v_add_u32_e32 v3, 1, v5
	s_nop 0
	v_cndmask_b32_e32 v1, v1, v4, vcc
	v_mul_lo_u32 v4, v2, v1
	v_add_u32_e32 v2, v4, v2
	v_cmp_ne_u32_e32 vcc, v3, v2
	s_and_saveexec_b64 s[12:13], vcc
	s_xor_b64 s[12:13], exec, s[12:13]
	s_cbranch_execz .Lseam1_342
	v_sub_u32_e32 v19, v2, v3
	v_cmp_eq_u32_e32 vcc, 1, v19
	s_cbranch_vccnz .Lpf3w_0
	v_cmp_eq_u32_e32 vcc, 4, v19
	s_cbranch_vccz .Lpf3_0
.Lpf3w_0:
	buffer_wbl2 sc1

; __device__ __forceinline__ unsigned xb_ld(unsigned* p)              { return __hip_atomic_load(p, __ATOMIC_RELAXED, __HIP_MEMORY_SCOPE_AGENT); }
; __device__ __forceinline__ unsigned xb_add(unsigned* p, unsigned v) { return __hip_atomic_fetch_add(p, v, __ATOMIC_RELAXED, __HIP_MEMORY_SCOPE_AGENT); }
; #define XB_SPIN(cond, bar) do { unsigned _sp = 0; while (cond) { __builtin_amdgcn_s_sleep(1); \
;     if ((++_sp & 255u) == 0u) { if (xb_ld(&(bar)[XB_TMO])) break; if (_sp > XB_SPIN_CAP) { atomicAdd(&(bar)[XB_TMO], 1u); break; } } } } while (0)
; __device__ __forceinline__ void xcd_barrier(const XcdBarrier& b, const int wv) {
;     ...
;         const unsigned old = xb_add(&bar[XB_XSUB(b.x)], 1u);
;         const unsigned gen = old / nloc;
;         if (old + 1u == (gen + 1u) * nloc) {
;             __builtin_amdgcn_fence(__ATOMIC_RELEASE, "agent");
;             asm volatile("s_waitcnt vmcnt(0)" ::: "memory");
;             const unsigned og = xb_add(&bar[XB_TOP], 1u);
;             const unsigned tg = og / nx;
;             if (og + 1u == (tg + 1u) * nx) xb_add(&bar[XB_TOPGEN], 1u);
;             else XB_SPIN(xb_ld(&bar[XB_TOPGEN]) == tg, bar);
;             __builtin_amdgcn_fence(__ATOMIC_ACQUIRE, "agent");
;             xb_add(&bar[XB_XGEN(b.x)], 1u);
;             asm volatile("s_waitcnt vmcnt(0)" ::: "memory");
;         } else {
;             XB_SPIN(xb_ld(&bar[XB_XGEN(b.x)]) == gen, bar);
;             __builtin_amdgcn_fence(__ATOMIC_ACQUIRE, "agent");
;             asm volatile("s_waitcnt vmcnt(0)" ::: "memory");
;         }
.LBB0_727:
	s_or_b64 exec, exec, s[16:17]
	v_cvt_f32_u32_e32 v4, v2
	s_waitcnt vmcnt(0)
	v_readfirstlane_b32 s3, v3
	v_sub_u32_e32 v3, 0, v2
	v_rcp_iflag_f32_e32 v4, v4
	v_add_u32_e32 v5, s3, v1
	v_mul_f32_e32 v4, 0x4f7ffffe, v4
	v_cvt_u32_f32_e32 v4, v4
	v_mul_lo_u32 v1, v3, v4
	v_mul_hi_u32 v1, v4, v1
	v_add_u32_e32 v1, v4, v1
	v_mul_hi_u32 v1, v5, v1
	v_mul_lo_u32 v3, v1, v2
	v_sub_u32_e32 v3, v5, v3
	v_add_u32_e32 v4, 1, v1
	v_cmp_ge_u32_e32 vcc, v3, v2
	s_nop 1
	v_cndmask_b32_e32 v1, v1, v4, vcc
	v_sub_u32_e32 v4, v3, v2
	v_cndmask_b32_e32 v3, v3, v4, vcc
	v_add_u32_e32 v4, 1, v1
	v_cmp_ge_u32_e32 vcc, v3, v2
	v_add_u32_e32 v3, 1, v5
	s_nop 0
	v_cndmask_b32_e32 v1, v1, v4, vcc
	v_mul_lo_u32 v4, v2, v1
	v_add_u32_e32 v2, v4, v2
	v_cmp_ne_u32_e32 vcc, v3, v2
	s_and_saveexec_b64 s[14:15], vcc
	s_xor_b64 s[14:15], exec, s[14:15]
	s_cbranch_execz .LBB0_741
	v_sub_u32_e32 v19, v2, v3
	v_cmp_eq_u32_e32 vcc, 1, v19
	s_cbranch_vccnz .Lpf3w_4
	v_cmp_eq_u32_e32 vcc, 4, v19
	s_cbranch_vccz .Lpf3_4

; __device__ __forceinline__ unsigned xb_ld(unsigned* p)              { return __hip_atomic_load(p, __ATOMIC_RELAXED, __HIP_MEMORY_SCOPE_AGENT); }
; __device__ __forceinline__ unsigned xb_add(unsigned* p, unsigned v) { return __hip_atomic_fetch_add(p, v, __ATOMIC_RELAXED, __HIP_MEMORY_SCOPE_AGENT); }
; #define XB_SPIN(cond, bar) do { unsigned _sp = 0; while (cond) { __builtin_amdgcn_s_sleep(1); \
;     if ((++_sp & 255u) == 0u) { if (xb_ld(&(bar)[XB_TMO])) break; if (_sp > XB_SPIN_CAP) { atomicAdd(&(bar)[XB_TMO], 1u); break; } } } } while (0)
; __device__ __forceinline__ void xcd_barrier(const XcdBarrier& b, const int wv) {
;     ...
;         const unsigned old = xb_add(&bar[XB_XSUB(b.x)], 1u);
;         const unsigned gen = old / nloc;
;         if (old + 1u == (gen + 1u) * nloc) {
;             __builtin_amdgcn_fence(__ATOMIC_RELEASE, "agent");
;             asm volatile("s_waitcnt vmcnt(0)" ::: "memory");
;             const unsigned og = xb_add(&bar[XB_TOP], 1u);
;             const unsigned tg = og / nx;
;             if (og + 1u == (tg + 1u) * nx) xb_add(&bar[XB_TOPGEN], 1u);
;             else XB_SPIN(xb_ld(&bar[XB_TOPGEN]) == tg, bar);
;             __builtin_amdgcn_fence(__ATOMIC_ACQUIRE, "agent");
;             xb_add(&bar[XB_XGEN(b.x)], 1u);
;             asm volatile("s_waitcnt vmcnt(0)" ::: "memory");
;         } else {
;             XB_SPIN(xb_ld(&bar[XB_XGEN(b.x)]) == gen, bar);
;             __builtin_amdgcn_fence(__ATOMIC_ACQUIRE, "agent");
;             asm volatile("s_waitcnt vmcnt(0)" ::: "memory");
;         }
.LBB0_860:
	s_or_b64 exec, exec, s[18:19]
	v_cvt_f32_u32_e32 v4, v2
	s_waitcnt vmcnt(0)
	v_readfirstlane_b32 s3, v3
	v_sub_u32_e32 v3, 0, v2
	v_rcp_iflag_f32_e32 v4, v4
	v_add_u32_e32 v5, s3, v1
	v_mul_f32_e32 v4, 0x4f7ffffe, v4
	v_cvt_u32_f32_e32 v4, v4
	v_mul_lo_u32 v1, v3, v4
	v_mul_hi_u32 v1, v4, v1
	v_add_u32_e32 v1, v4, v1
	v_mul_hi_u32 v1, v5, v1
	v_mul_lo_u32 v3, v1, v2
	v_sub_u32_e32 v3, v5, v3
	v_add_u32_e32 v4, 1, v1
	v_cmp_ge_u32_e32 vcc, v3, v2
	s_nop 1
	v_cndmask_b32_e32 v1, v1, v4, vcc
	v_sub_u32_e32 v4, v3, v2
	v_cndmask_b32_e32 v3, v3, v4, vcc
	v_add_u32_e32 v4, 1, v1
	v_cmp_ge_u32_e32 vcc, v3, v2
	v_add_u32_e32 v3, 1, v5
	s_nop 0
	v_cndmask_b32_e32 v1, v1, v4, vcc
	v_mul_lo_u32 v4, v2, v1
	v_add_u32_e32 v2, v4, v2
	v_cmp_ne_u32_e32 vcc, v3, v2
	s_and_saveexec_b64 s[16:17], vcc
	s_xor_b64 s[16:17], exec, s[16:17]
	s_cbranch_execz .LBB0_874
	v_sub_u32_e32 v19, v2, v3
	v_cmp_eq_u32_e32 vcc, 1, v19
	s_cbranch_vccnz .Lpf3w_6
	v_cmp_eq_u32_e32 vcc, 4, v19
	s_cbranch_vccz .Lpf3_6
